# attention K/V tiles staged by LDS-DMA into a dense source-swizzled LDS image (no register staging, no ds_write)
# speedup vs baseline: 1.0171x; 1.0171x over previous
.LBB0_1332:
	v_and_b32_e32 v85, 64, v193
	ds_read_b128 v[72:75], v144
	ds_read_b128 v[76:79], v144 offset:4096
	ds_read_b128 v[80:83], v145
	v_xor_b32_e32 v84, 32, v193
	v_add_u32_e32 v85, 64, v85
	v_cmp_lt_i32_e32 vcc, v84, v85
	s_waitcnt lgkmcnt(2)
	v_mfma_f32_32x32x16_bf16 v[48:63], v[72:75], v[68:71], v[48:63]
	s_add_i32 s97, s97, s91
	v_cndmask_b32_e32 v84, v193, v84, vcc
	v_lshlrev_b32_e32 v72, 2, v84
	ds_bpermute_b32 v88, v72, v200
	ds_read_b128 v[72:75], v144 offset:8192
	ds_read_b128 v[84:87], v145 offset:4096
	s_add_i32 s96, s96, 1
	s_cmp_eq_u32 s96, 4
	s_waitcnt lgkmcnt(4)
	v_mfma_f32_32x32x16_bf16 v[32:47], v[76:79], v[68:71], v[32:47]
	s_waitcnt lgkmcnt(2)
	v_add_f32_e32 v96, v200, v88
	ds_read_b128 v[76:79], v145 offset:8192
	ds_read_b128 v[88:91], v144 offset:12288
	ds_read_b128 v[92:95], v145 offset:12288
	v_div_scale_f32 v97, s[0:1], v96, v96, 1.0
	v_rcp_f32_e32 v98, v97
	s_nop 0
	v_fma_f32 v99, -v97, v98, 1.0
	s_waitcnt lgkmcnt(4)
	v_mfma_f32_32x32x16_bf16 v[16:31], v[72:75], v[68:71], v[16:31]
	v_fmac_f32_e32 v98, v99, v98
	v_div_scale_f32 v72, vcc, 1.0, v96, 1.0
	v_mul_f32_e32 v73, v72, v98
	v_fma_f32 v74, -v97, v73, v72
	v_fmac_f32_e32 v73, v74, v98
	v_fma_f32 v72, -v97, v73, v72
	s_waitcnt lgkmcnt(1)
	v_mfma_f32_32x32x16_bf16 v[0:15], v[88:91], v[68:71], v[0:15]
	v_mov_b32_e32 v69, v191
	v_div_fmas_f32 v68, v72, v98, v73
	v_and_or_b32 v70, v69, 31, s97
	v_ashrrev_i32_e32 v71, 31, v70
	v_div_fixup_f32 v68, v68, v96, 1.0
	v_lshlrev_b64 v[70:71], 11, v[70:71]
	v_mfma_f32_32x32x16_bf16 v[48:63], v[80:83], v[64:67], v[48:63]
	v_lshrrev_b32_e32 v69, 2, v69
	v_lshl_add_u64 v[70:71], s[70:71], 0, v[70:71]
	v_and_b32_e32 v180, 8, v69
	v_lshl_add_u64 v[70:71], v[70:71], 0, v[180:181]
	v_mfma_f32_32x32x16_bf16 v[32:47], v[84:87], v[64:67], v[32:47]
	s_nop 6
	v_mul_f32_e64 v48, v48, v68
	v_mul_f32_e64 v49, v49, v68
	v_mul_f32_e64 v50, v50, v68
	v_mul_f32_e64 v51, v51, v68
	v_cvt_pk_bf16_f32 v48, v48, v49
	v_cvt_pk_bf16_f32 v49, v50, v51
	global_store_dwordx2 v[70:71], v[48:49], off
	v_pk_mul_f32 v[48:49], v[52:53], v[68:69] op_sel_hi:[1,0]
	v_pk_mul_f32 v[50:51], v[54:55], v[68:69] op_sel_hi:[1,0]
	v_mfma_f32_32x32x16_bf16 v[16:31], v[76:79], v[64:67], v[16:31]
	v_mul_f32_e64 v32, v32, v68
	v_mul_f32_e64 v33, v33, v68
	v_mul_f32_e64 v34, v34, v68
	v_mul_f32_e64 v35, v35, v68
	v_cvt_pk_bf16_f32 v32, v32, v33
	v_cvt_pk_bf16_f32 v33, v34, v35
	global_store_dwordx2 v[70:71], v[32:33], off offset:64
	v_pk_mul_f32 v[32:33], v[36:37], v[68:69] op_sel_hi:[1,0]
	v_pk_mul_f32 v[34:35], v[38:39], v[68:69] op_sel_hi:[1,0]
	s_waitcnt lgkmcnt(0)
	v_mfma_f32_32x32x16_bf16 v[0:15], v[92:95], v[64:67], v[0:15]
	s_nop 0
	v_mul_f32_e64 v16, v16, v68
	v_mul_f32_e64 v17, v17, v68
	v_mul_f32_e64 v18, v18, v68
	v_mul_f32_e64 v19, v19, v68
	v_cvt_pk_bf16_f32 v16, v16, v17
	v_cvt_pk_bf16_f32 v17, v18, v19
	global_store_dwordx2 v[70:71], v[16:17], off offset:128
	v_pk_mul_f32 v[16:17], v[20:21], v[68:69] op_sel_hi:[1,0]
	v_pk_mul_f32 v[18:19], v[22:23], v[68:69] op_sel_hi:[1,0]
	s_nop 1
	v_pk_mul_f32 v[0:1], v[0:1], v[68:69] op_sel_hi:[1,0]
	v_pk_mul_f32 v[2:3], v[2:3], v[68:69] op_sel_hi:[1,0]
	v_cvt_pk_bf16_f32 v0, v0, v1
	v_cvt_pk_bf16_f32 v1, v2, v3
	global_store_dwordx2 v[70:71], v[0:1], off offset:192
	v_pk_mul_f32 v[0:1], v[4:5], v[68:69] op_sel_hi:[1,0]
	v_pk_mul_f32 v[2:3], v[6:7], v[68:69] op_sel_hi:[1,0]
	v_cvt_pk_bf16_f32 v48, v48, v49
	v_cvt_pk_bf16_f32 v49, v50, v51
	v_cvt_pk_bf16_f32 v32, v32, v33
	v_cvt_pk_bf16_f32 v33, v34, v35
	v_cvt_pk_bf16_f32 v16, v16, v17
	v_cvt_pk_bf16_f32 v17, v18, v19
	v_cvt_pk_bf16_f32 v0, v0, v1
	v_cvt_pk_bf16_f32 v1, v2, v3
	global_store_dwordx2 v[70:71], v[48:49], off offset:16
	v_pk_mul_f32 v[48:49], v[56:57], v[68:69] op_sel_hi:[1,0]
	v_pk_mul_f32 v[50:51], v[58:59], v[68:69] op_sel_hi:[1,0]
	global_store_dwordx2 v[70:71], v[32:33], off offset:80
	v_pk_mul_f32 v[32:33], v[40:41], v[68:69] op_sel_hi:[1,0]
	v_pk_mul_f32 v[34:35], v[42:43], v[68:69] op_sel_hi:[1,0]
	global_store_dwordx2 v[70:71], v[16:17], off offset:144
	v_pk_mul_f32 v[16:17], v[24:25], v[68:69] op_sel_hi:[1,0]
	v_pk_mul_f32 v[18:19], v[26:27], v[68:69] op_sel_hi:[1,0]
	global_store_dwordx2 v[70:71], v[0:1], off offset:208
	v_pk_mul_f32 v[0:1], v[8:9], v[68:69] op_sel_hi:[1,0]
	v_pk_mul_f32 v[2:3], v[10:11], v[68:69] op_sel_hi:[1,0]
	v_cvt_pk_bf16_f32 v48, v48, v49
	v_cvt_pk_bf16_f32 v49, v50, v51
	v_cvt_pk_bf16_f32 v32, v32, v33
	v_cvt_pk_bf16_f32 v33, v34, v35
	v_cvt_pk_bf16_f32 v16, v16, v17
	v_cvt_pk_bf16_f32 v17, v18, v19
	v_cvt_pk_bf16_f32 v0, v0, v1
	v_cvt_pk_bf16_f32 v1, v2, v3
	global_store_dwordx2 v[70:71], v[48:49], off offset:32
	v_pk_mul_f32 v[48:49], v[60:61], v[68:69] op_sel_hi:[1,0]
	v_pk_mul_f32 v[50:51], v[62:63], v[68:69] op_sel_hi:[1,0]
	global_store_dwordx2 v[70:71], v[32:33], off offset:96
	v_pk_mul_f32 v[32:33], v[44:45], v[68:69] op_sel_hi:[1,0]
	v_pk_mul_f32 v[34:35], v[46:47], v[68:69] op_sel_hi:[1,0]
	global_store_dwordx2 v[70:71], v[16:17], off offset:160
	v_pk_mul_f32 v[16:17], v[28:29], v[68:69] op_sel_hi:[1,0]
	v_pk_mul_f32 v[18:19], v[30:31], v[68:69] op_sel_hi:[1,0]
	global_store_dwordx2 v[70:71], v[0:1], off offset:224
	v_pk_mul_f32 v[0:1], v[12:13], v[68:69] op_sel_hi:[1,0]
	v_pk_mul_f32 v[2:3], v[14:15], v[68:69] op_sel_hi:[1,0]
	v_cvt_pk_bf16_f32 v48, v48, v49
	v_cvt_pk_bf16_f32 v49, v50, v51
	v_cvt_pk_bf16_f32 v32, v32, v33
	v_cvt_pk_bf16_f32 v33, v34, v35
	v_cvt_pk_bf16_f32 v16, v16, v17
	v_cvt_pk_bf16_f32 v17, v18, v19
	v_cvt_pk_bf16_f32 v0, v0, v1
	v_cvt_pk_bf16_f32 v1, v2, v3
	global_store_dwordx2 v[70:71], v[48:49], off offset:48
	global_store_dwordx2 v[70:71], v[32:33], off offset:112
	global_store_dwordx2 v[70:71], v[16:17], off offset:176
	global_store_dwordx2 v[70:71], v[0:1], off offset:240
	s_barrier
	s_cbranch_scc1 .LBB0_1329

.LBB0_1338:
	v_mov_b32_e32 v54, v191
	s_lshl_b32 s97, s4, 8
	s_add_i32 s97, s97, s79
	v_and_b32_e32 v48, 31, v54
	v_or_b32_e32 v0, s97, v48
	v_ashrrev_i32_e32 v50, 3, v54
	v_and_b32_e32 v56, 7, v54
	v_bfe_u32 v49, v54, 5, 1
	v_add_u32_e32 v0, s91, v0
	s_movk_i32 s0, 0xc00
	v_ashrrev_i32_e32 v51, 4, v54
	v_and_b32_e32 v55, 15, v54
	v_add_u32_e32 v9, s91, v50
	v_lshlrev_b32_e32 v52, 3, v56
	v_and_b32_e32 v172, 7, v51
	v_lshlrev_b32_e32 v172, 3, v172
	v_xor_b32_e32 v52, v172, v52
	v_ashrrev_i32_e32 v1, 31, v0
	v_mad_i64_i32 v[2:3], s[0:1], v0, s0, v[182:183]
	v_lshlrev_b32_e32 v180, 4, v49
	v_add_lshl_u32 v8, v51, s91, 10
	v_lshlrev_b32_e32 v53, 3, v55
	v_and_b32_e32 v172, 15, v51
	v_lshlrev_b32_e32 v172, 3, v172
	v_xor_b32_e32 v53, v172, v53
	v_lshl_or_b32 v10, v9, 6, v52
	v_add_lshl_u32 v9, v50, s92, 15
	v_lshl_add_u64 v[24:25], v[2:3], 0, v[180:181]
	v_lshlrev_b64 v[0:1], 7, v[0:1]
	v_or3_b32 v8, v8, v53, s92
	v_or3_b32 v12, v9, s91, v52
	v_add_lshl_u32 v234, v50, s92, 11
	v_add_u32_e32 v12, v12, v234
	v_mov_b32_e32 v9, v181
	global_load_dwordx4 v[96:99], v[24:25], off
	global_load_dwordx4 v[100:103], v[24:25], off offset:32
	global_load_dwordx4 v[104:107], v[24:25], off offset:64
	global_load_dwordx4 v[108:111], v[24:25], off offset:96
	global_load_dwordx4 v[112:115], v[24:25], off offset:128
	global_load_dwordx4 v[116:119], v[24:25], off offset:160
	global_load_dwordx4 v[120:123], v[24:25], off offset:192
	global_load_dwordx4 v[124:127], v[24:25], off offset:224
	v_lshl_add_u64 v[2:3], s[62:63], 0, v[0:1]
	v_lshlrev_b32_e32 v4, 5, v49
	v_mov_b32_e32 v5, v181
	v_lshl_add_u64 v[14:15], v[8:9], 1, s[64:65]
	v_add_u32_e32 v8, 0x8000, v8
	v_lshl_add_u64 v[28:29], v[2:3], 0, v[4:5]
	v_lshl_add_u64 v[0:1], s[66:67], 0, v[0:1]
	v_lshl_add_u64 v[8:9], v[8:9], 1, s[64:65]
	v_mov_b32_e32 v11, v181
	v_lshl_add_u64 v[44:45], v[0:1], 0, v[4:5]
	global_load_dwordx4 v[0:3], v[28:29], off offset:16
	global_load_dwordx4 v[4:7], v[28:29], off
	s_and_b32 s5, s97, 0xe0
	s_lshl_b32 s5, s5, 5
	s_mov_b32 m0, s5
	s_nop 0
	global_load_lds_dwordx4 v[14:15], off
	s_add_i32 m0, s5, 0x2000
	s_nop 0
	global_load_lds_dwordx4 v[8:9], off
	v_lshl_add_u64 v[8:9], v[10:11], 1, s[60:61]
	v_mov_b32_e32 v13, v181
	v_lshl_add_u64 v[10:11], v[12:13], 1, s[68:69]
	s_add_i32 m0, s5, 0x8000
	s_nop 0
	global_load_lds_dwordx4 v[8:9], off
	s_add_i32 m0, s5, 0xc000
	s_nop 0
	global_load_lds_dwordx4 v[10:11], off
	v_add_u32_e32 v8, 0x220000, v12
	v_mov_b32_e32 v9, v181
	v_lshl_add_u64 v[8:9], v[8:9], 1, s[68:69]
	s_add_i32 m0, s5, 0xe000
	s_nop 0
	global_load_lds_dwordx4 v[8:9], off
	s_nop 0
	global_load_dwordx4 v[8:11], v[44:45], off offset:16
	global_load_dwordx4 v[20:23], v[44:45], off
	global_load_dwordx4 v[12:15], v[24:25], off offset:256
	global_load_dwordx4 v[32:35], v[24:25], off offset:288
	global_load_dwordx4 v[16:19], v[24:25], off offset:320
	global_load_dwordx4 v[36:39], v[24:25], off offset:352
	s_nop 0
	global_load_dwordx4 v[24:27], v[28:29], off offset:80
	global_load_dwordx4 v[40:43], v[28:29], off offset:64
	s_nop 0
	global_load_dwordx4 v[28:31], v[44:45], off offset:80
	s_nop 0
	global_load_dwordx4 v[44:47], v[44:45], off offset:64
	v_lshlrev_b32_e32 v57, 3, v54
	v_mul_lo_u32 v58, v51, s82
	v_lshlrev_b32_e32 v54, 4, v56
	v_mul_lo_u32 v56, v50, s83
	v_lshl_add_u32 v194, v55, 4, v58
	v_and_b32_e32 v55, 0x60, v54
	v_and_b32_e32 v57, 8, v57
	v_mad_u64_u32 v[184:185], s[0:1], v50, s82, v[54:55]
	v_add_u32_e32 v54, 0, v56
	v_add3_u32 v185, v54, v57, v55
	v_add_u32_e32 v56, 0, v194
	v_add_u32_e32 v54, 0xc800, v185
	v_add_u32_e32 v58, 0, v184
	v_add_u32_e32 v55, 0xe800, v185
	s_cmp_lt_i32 s4, 0
	s_mov_b32 s52, 0
	s_waitcnt vmcnt(0)
	v_mad_u32_u24 v54, v48, s83, 0
	v_add_u32_e32 v195, v54, v180
	v_and_b32_e32 v172, 0x13, v48
	v_and_b32_e32 v175, 4, v48
	v_lshl_or_b32 v172, v175, 1, v172
	v_and_b32_e32 v175, 8, v48
	v_lshrrev_b32_e32 v175, 1, v175
	v_or_b32_e32 v172, v172, v175
	v_and_b32_e32 v175, 15, v172
	v_xor_b32_e32 v175, v175, v49
	v_lshlrev_b32_e32 v175, 4, v175
	v_lshl_or_b32 v128, v172, 8, v175
	v_xor_b32_e32 v129, 0x20, v128
	v_xor_b32_e32 v130, 0x40, v128
	v_xor_b32_e32 v131, 0x60, v128
	v_xor_b32_e32 v132, 0x80, v128
	v_xor_b32_e32 v133, 0xa0, v128
	v_xor_b32_e32 v134, 0xc0, v128
	v_xor_b32_e32 v135, 0xe0, v128
	v_bfe_u32 v175, v172, 1, 3
	v_xor_b32_e32 v175, v175, v49
	v_lshlrev_b32_e32 v175, 4, v175
	v_lshl_or_b32 v136, v172, 7, v175
	v_add_u32_e32 v136, 0x8000, v136
	v_xor_b32_e32 v137, 0x20, v136
	v_xor_b32_e32 v138, 0x40, v136
	v_xor_b32_e32 v139, 0x60, v136
	v_bfe_u32 v175, v48, 1, 3
	v_xor_b32_e32 v175, v175, v49
	v_lshlrev_b32_e32 v175, 4, v175
	v_lshl_or_b32 v140, v48, 7, v175
	v_add_u32_e32 v140, 0xc000, v140
	v_xor_b32_e32 v141, 32, v140
	v_xor_b32_e32 v144, 64, v140
	v_xor_b32_e32 v145, 64, v141
	s_waitcnt lgkmcnt(0)
	s_barrier
	s_cbranch_scc1 .LBB0_1331
	v_lshlrev_b32_e32 v55, 8, v48
	v_add3_u32 v196, v54, v55, v180
	v_and_b32_e32 v55, 0xffff0000, v36
	v_lshlrev_b32_e32 v54, 16, v36
	v_and_b32_e32 v57, 0xffff0000, v32
	v_lshlrev_b32_e32 v56, 16, v32
	v_pk_mul_f32 v[58:59], v[44:45], v[56:57]
	v_pk_mul_f32 v[44:45], v[44:45], v[54:55]
	v_pk_fma_f32 v[58:59], v[40:41], v[54:55], v[58:59]
	v_pk_fma_f32 v[40:41], v[40:41], v[56:57], v[44:45] neg_lo:[0,0,1] neg_hi:[0,0,1]
	v_lshlrev_b32_e32 v36, 16, v33
	v_cvt_pk_bf16_f32 v152, v40, v41
	v_and_b32_e32 v41, 0xffff0000, v37
	v_lshlrev_b32_e32 v40, 16, v37
	v_and_b32_e32 v37, 0xffff0000, v33
	v_pk_mul_f32 v[32:33], v[46:47], v[36:37]
	s_lshl_b32 s53, s4, 2
	v_pk_fma_f32 v[32:33], v[42:43], v[40:41], v[32:33]
	v_mov_b32_e32 v200, 0
	v_cvt_pk_bf16_f32 v149, v32, v33
	v_pk_mul_f32 v[32:33], v[46:47], v[40:41]
	s_add_i32 s53, s53, 4
	v_pk_fma_f32 v[32:33], v[42:43], v[36:37], v[32:33] neg_lo:[0,0,1] neg_hi:[0,0,1]
	v_and_b32_e32 v37, 0xffff0000, v34
	v_cvt_pk_bf16_f32 v153, v32, v33
	v_and_b32_e32 v33, 0xffff0000, v38
	v_lshlrev_b32_e32 v32, 16, v38
	v_lshlrev_b32_e32 v36, 16, v34
	v_pk_mul_f32 v[40:41], v[28:29], v[36:37]
	v_pk_mul_f32 v[28:29], v[28:29], v[32:33]
	v_pk_fma_f32 v[40:41], v[24:25], v[32:33], v[40:41]
	v_pk_fma_f32 v[24:25], v[24:25], v[36:37], v[28:29] neg_lo:[0,0,1] neg_hi:[0,0,1]
	v_and_b32_e32 v29, 0xffff0000, v35
	v_lshlrev_b32_e32 v28, 16, v35
	v_cvt_pk_bf16_f32 v154, v24, v25
	v_and_b32_e32 v25, 0xffff0000, v39
	v_lshlrev_b32_e32 v24, 16, v39
	v_pk_mul_f32 v[32:33], v[30:31], v[28:29]
	v_cvt_pk_bf16_f32 v148, v58, v59
	v_pk_fma_f32 v[32:33], v[26:27], v[24:25], v[32:33]
	v_pk_mul_f32 v[24:25], v[30:31], v[24:25]
	v_cvt_pk_bf16_f32 v150, v40, v41
	v_pk_fma_f32 v[24:25], v[26:27], v[28:29], v[24:25] neg_lo:[0,0,1] neg_hi:[0,0,1]
	v_and_b32_e32 v27, 0xffff0000, v12
	v_cvt_pk_bf16_f32 v155, v24, v25
	v_and_b32_e32 v25, 0xffff0000, v16
	v_lshlrev_b32_e32 v24, 16, v16
	v_lshlrev_b32_e32 v26, 16, v12
	v_pk_mul_f32 v[28:29], v[20:21], v[26:27]
	v_pk_mul_f32 v[20:21], v[20:21], v[24:25]
	v_pk_fma_f32 v[28:29], v[4:5], v[24:25], v[28:29]
	v_pk_fma_f32 v[4:5], v[4:5], v[26:27], v[20:21] neg_lo:[0,0,1] neg_hi:[0,0,1]
	v_lshlrev_b32_e32 v16, 16, v13
	v_cvt_pk_bf16_f32 v160, v4, v5
	v_and_b32_e32 v5, 0xffff0000, v17
	v_lshlrev_b32_e32 v4, 16, v17
	v_and_b32_e32 v17, 0xffff0000, v13
	v_pk_mul_f32 v[12:13], v[22:23], v[16:17]
	v_cvt_pk_bf16_f32 v151, v32, v33
	v_pk_fma_f32 v[12:13], v[6:7], v[4:5], v[12:13]
	v_pk_mul_f32 v[4:5], v[22:23], v[4:5]
	v_cvt_pk_bf16_f32 v157, v12, v13
	v_pk_fma_f32 v[4:5], v[6:7], v[16:17], v[4:5] neg_lo:[0,0,1] neg_hi:[0,0,1]
	v_and_b32_e32 v7, 0xffff0000, v14
	v_lshlrev_b32_e32 v6, 16, v14
	v_cvt_pk_bf16_f32 v161, v4, v5
	v_and_b32_e32 v5, 0xffff0000, v18
	v_lshlrev_b32_e32 v4, 16, v18
	v_pk_mul_f32 v[12:13], v[8:9], v[6:7]
	v_cvt_pk_bf16_f32 v156, v28, v29
	v_pk_fma_f32 v[12:13], v[0:1], v[4:5], v[12:13]
	v_pk_mul_f32 v[4:5], v[8:9], v[4:5]
	v_cvt_pk_bf16_f32 v158, v12, v13
	v_pk_fma_f32 v[0:1], v[0:1], v[6:7], v[4:5] neg_lo:[0,0,1] neg_hi:[0,0,1]
	v_and_b32_e32 v5, 0xffff0000, v15
	v_lshlrev_b32_e32 v4, 16, v15
	v_cvt_pk_bf16_f32 v162, v0, v1
	v_and_b32_e32 v1, 0xffff0000, v19
	v_lshlrev_b32_e32 v0, 16, v19
	v_pk_mul_f32 v[6:7], v[10:11], v[4:5]
	v_mov_b32_e32 v199, 0xf149f2ca
	v_pk_fma_f32 v[6:7], v[2:3], v[0:1], v[6:7]
	v_pk_mul_f32 v[0:1], v[10:11], v[0:1]
	v_cvt_pk_bf16_f32 v159, v6, v7
	v_pk_fma_f32 v[0:1], v[2:3], v[4:5], v[0:1] neg_lo:[0,0,1] neg_hi:[0,0,1]
	s_mov_b32 s33, 63
	v_cvt_pk_bf16_f32 v163, v0, v1
	v_lshlrev_b32_e32 v1, 10, v51
	v_lshlrev_b32_e32 v0, 3, v49
	v_add3_u32 v186, s93, v1, v53
	v_add_u32_e32 v1, s97, v48
	v_sub_u32_e32 v197, v1, v0
	v_lshlrev_b32_e32 v0, 6, v50
	v_add3_u32 v188, s94, v0, v52
	v_lshlrev_b32_e32 v0, 15, v50
	v_add3_u32 v198, s95, v0, v52
	v_add_lshl_u32 v234, v50, s92, 11
	v_add_u32_e32 v198, v198, v234
	v_mov_b32_e32 v64, 0
	v_mov_b32_e32 v65, 0
	v_mov_b32_e32 v66, 0
	v_mov_b32_e32 v67, 0
	v_mov_b32_e32 v68, 0
	v_mov_b32_e32 v69, 0
	v_mov_b32_e32 v70, 0
	v_mov_b32_e32 v71, 0
	s_mov_b32 s0, 0
	v_mov_b32_e32 v0, 0
	v_mov_b32_e32 v1, v200
	v_mov_b32_e32 v2, v200
	v_mov_b32_e32 v3, v200
	v_mov_b32_e32 v4, v200
	v_mov_b32_e32 v5, v200
	v_mov_b32_e32 v6, v200
	v_mov_b32_e32 v7, v200
	v_mov_b32_e32 v8, v200
	v_mov_b32_e32 v9, v200
	v_mov_b32_e32 v10, v200
	v_mov_b32_e32 v11, v200
	v_mov_b32_e32 v12, v200
	v_mov_b32_e32 v13, v200
	v_mov_b32_e32 v14, v200
	v_mov_b32_e32 v15, v200
	v_mov_b32_e32 v16, 0
	v_mov_b32_e32 v17, v200
	v_mov_b32_e32 v18, v200
	v_mov_b32_e32 v19, v200
	v_mov_b32_e32 v20, v200
	v_mov_b32_e32 v21, v200
	v_mov_b32_e32 v22, v200
	v_mov_b32_e32 v23, v200
	v_mov_b32_e32 v24, v200
	v_mov_b32_e32 v25, v200
	v_mov_b32_e32 v26, v200
	v_mov_b32_e32 v27, v200
	v_mov_b32_e32 v28, v200
	v_mov_b32_e32 v29, v200
	v_mov_b32_e32 v30, v200
	v_mov_b32_e32 v31, v200
	v_mov_b32_e32 v32, 0
	v_mov_b32_e32 v33, v200
	v_mov_b32_e32 v34, v200
	v_mov_b32_e32 v35, v200
	v_mov_b32_e32 v36, v200
	v_mov_b32_e32 v37, v200
	v_mov_b32_e32 v38, v200
	v_mov_b32_e32 v39, v200
	v_mov_b32_e32 v40, v200
	v_mov_b32_e32 v41, v200
	v_mov_b32_e32 v42, v200
	v_mov_b32_e32 v43, v200
	v_mov_b32_e32 v44, v200
	v_mov_b32_e32 v45, v200
	v_mov_b32_e32 v46, v200
	v_mov_b32_e32 v47, v200
	v_mov_b32_e32 v48, 0
	v_mov_b32_e32 v49, v200
	v_mov_b32_e32 v50, v200
	v_mov_b32_e32 v51, v200
	v_mov_b32_e32 v52, v200
	v_mov_b32_e32 v53, v200
	v_mov_b32_e32 v54, v200
	v_mov_b32_e32 v55, v200
	v_mov_b32_e32 v56, v200
	v_mov_b32_e32 v57, v200
	v_mov_b32_e32 v58, v200
	v_mov_b32_e32 v59, v200
	v_mov_b32_e32 v60, v200
	v_mov_b32_e32 v61, v200
	v_mov_b32_e32 v62, v200
	v_mov_b32_e32 v63, v200
	s_mov_b32 s55, 0
	v_xor_b32_e32 v246, 32, v193
	v_lshlrev_b32_e32 v246, 2, v246
	v_mov_b32_e32 v64, 0xff61b1e6
	v_mov_b32_e32 v65, v64
	v_mov_b32_e32 v66, v64
	v_mov_b32_e32 v67, v64
	v_mov_b32_e32 v68, v64
	v_mov_b32_e32 v69, v64
	v_mov_b32_e32 v70, v64
	v_mov_b32_e32 v71, v64
	v_mov_b32_e32 v72, v64
	v_mov_b32_e32 v73, v64
	v_mov_b32_e32 v74, v64
	v_mov_b32_e32 v75, v64
	v_mov_b32_e32 v76, v64
	v_mov_b32_e32 v77, v64
	v_mov_b32_e32 v78, v64
	v_mov_b32_e32 v79, v64
	v_add_u32_e32 v201, 0xfffe8000, v186
	v_lshlrev_b32_e32 v201, 1, v201
	v_add_u32_e32 v230, 0x10000, v201
	v_add_u32_e32 v231, 0xfffff000, v188
	v_lshlrev_b32_e32 v231, 1, v231
	v_lshlrev_b32_e32 v232, 1, v198
	v_add_u32_e32 v233, 0x440000, v232
	s_mov_b64 s[20:21], s[64:65]
	s_mov_b64 s[22:23], s[60:61]
	s_mov_b64 s[24:25], s[68:69]
.LBB0_1340:
	s_add_i32 s54, s0, 1
	s_cmp_lt_i32 s54, s53
	s_cbranch_scc0 .Lat_skip_ld
	s_add_u32 s20, s20, 0x20000
	s_addc_u32 s21, s21, 0
	s_add_u32 s22, s22, 0x2000
	s_addc_u32 s23, s23, 0
	s_add_u32 s24, s24, 0x80
	s_addc_u32 s25, s25, 0
	s_and_b32 s5, s97, 0xe0
	s_lshl_b32 s5, s5, 5
	s_bitcmp1_b32 s54, 0
	s_cselect_b32 s4, 0x4000, 0
	s_lshr_b32 s6, s4, 1
	s_add_i32 s4, s4, s5
	s_add_i32 s6, s6, s5
	s_add_i32 s6, s6, 0x8000
	s_mov_b32 m0, s4
	s_add_i32 s7, s52, 1
	s_cmp_lg_u32 s52, 2
	s_cselect_b32 s7, s7, 0
	s_lshl_b32 s7, s7, 14
	global_load_lds_dwordx4 v201, s[20:21]
	s_add_i32 m0, s4, 0x2000
	s_add_i32 s7, s7, s5
	global_load_lds_dwordx4 v230, s[20:21]
	s_mov_b32 m0, s6
	s_add_i32 s7, s7, 0xc000
	global_load_lds_dwordx4 v231, s[22:23]
	s_mov_b32 m0, s7
	s_nop 0
	global_load_lds_dwordx4 v232, s[24:25]
	s_add_i32 m0, s7, 0x2000
	s_nop 0
	global_load_lds_dwordx4 v233, s[24:25]
.Lat_skip_ld:
	s_add_i32 s4, s97, 94
	s_cmp_gt_i32 s33, s4
	s_cbranch_scc1 .Lat_idle
	ds_read_b128 v[202:205], v128
	ds_read_b128 v[206:209], v129
	ds_read_b128 v[210:213], v130
	ds_read_b128 v[214:217], v131
	ds_read_b128 v[218:221], v132
	ds_read_b128 v[222:225], v133
	v_fma_f32 v64, v64, s84, -v199
	v_exp_f32_e32 v64, v64
	v_fma_f32 v65, v65, s84, -v199
	v_exp_f32_e32 v65, v65
	v_add_f32_e32 v200, v200, v64
	v_fma_f32 v66, v66, s84, -v199
	v_exp_f32_e32 v66, v66
	v_add_f32_e32 v200, v200, v65
	s_waitcnt lgkmcnt(4)
	v_mfma_f32_32x32x16_bf16 v[80:95], v[202:205], v[96:99], 0
	ds_read_b128 v[202:205], v134
	v_fma_f32 v67, v67, s84, -v199
	v_exp_f32_e32 v67, v67
	v_add_f32_e32 v200, v200, v66
	v_fma_f32 v68, v68, s84, -v199
	v_mfma_f32_32x32x16_bf16 v[80:95], v[206:209], v[100:103], v[80:95]
	ds_read_b128 v[206:209], v135
	v_exp_f32_e32 v68, v68
	v_add_f32_e32 v200, v200, v67
	v_fma_f32 v69, v69, s84, -v199
	v_exp_f32_e32 v69, v69
	s_waitcnt lgkmcnt(4)
	v_mfma_f32_32x32x16_bf16 v[80:95], v[210:213], v[104:107], v[80:95]
	ds_read_b128 v[210:213], v136
	v_add_f32_e32 v200, v200, v68
	v_fma_f32 v70, v70, s84, -v199
	v_exp_f32_e32 v70, v70
	v_add_f32_e32 v200, v200, v69
	v_mfma_f32_32x32x16_bf16 v[80:95], v[214:217], v[108:111], v[80:95]
	ds_read_b128 v[214:217], v137
	v_fma_f32 v71, v71, s84, -v199
	v_exp_f32_e32 v71, v71
	v_add_f32_e32 v200, v200, v70
	v_fma_f32 v72, v72, s84, -v199
	s_waitcnt lgkmcnt(4)
	v_mfma_f32_32x32x16_bf16 v[80:95], v[218:221], v[112:115], v[80:95]
	ds_read_b128 v[218:221], v138
	v_exp_f32_e32 v72, v72
	v_add_f32_e32 v200, v200, v71
	v_fma_f32 v73, v73, s84, -v199
	v_exp_f32_e32 v73, v73
	v_mfma_f32_32x32x16_bf16 v[80:95], v[222:225], v[116:119], v[80:95]
	ds_read_b128 v[222:225], v139
	v_add_f32_e32 v200, v200, v72
	v_fma_f32 v74, v74, s84, -v199
	v_exp_f32_e32 v74, v74
	v_add_f32_e32 v200, v200, v73
	s_waitcnt lgkmcnt(4)
	v_mfma_f32_32x32x16_bf16 v[80:95], v[202:205], v[120:123], v[80:95]
	ds_read_b128 v[164:167], v144
	v_fma_f32 v75, v75, s84, -v199
	v_exp_f32_e32 v75, v75
	v_add_f32_e32 v200, v200, v74
	v_fma_f32 v76, v76, s84, -v199
	v_mfma_f32_32x32x16_bf16 v[80:95], v[206:209], v[124:127], v[80:95]
	ds_read_b128 v[168:171], v144 offset:4096
	v_exp_f32_e32 v76, v76
	v_add_f32_e32 v200, v200, v75
	v_fma_f32 v77, v77, s84, -v199
	v_exp_f32_e32 v77, v77
	s_waitcnt lgkmcnt(4)
	v_mfma_f32_32x32x16_bf16 v[80:95], v[210:213], v[160:163], v[80:95]
	ds_read_b128 v[176:179], v144 offset:8192
	v_add_f32_e32 v200, v200, v76
	v_fma_f32 v78, v78, s84, -v199
	v_exp_f32_e32 v78, v78
	v_add_f32_e32 v200, v200, v77
	v_mfma_f32_32x32x16_bf16 v[80:95], v[214:217], v[152:155], v[80:95]
	ds_read_b128 v[226:229], v144 offset:12288
	v_fma_f32 v79, v79, s84, -v199
	v_exp_f32_e32 v79, v79
	v_add_f32_e32 v200, v200, v78
	v_add_f32_e32 v200, v200, v79
	s_waitcnt lgkmcnt(4)
	v_mfma_f32_32x32x16_bf16 v[80:95], v[218:221], v[156:159], v[80:95]
	v_cvt_pk_bf16_f32 v64, v64, v65
	v_cvt_pk_bf16_f32 v65, v66, v67
	v_cvt_pk_bf16_f32 v66, v68, v69
	v_cvt_pk_bf16_f32 v67, v70, v71
	v_mfma_f32_32x32x16_bf16 v[80:95], v[222:225], v[148:151], v[80:95]
	v_cvt_pk_bf16_f32 v68, v72, v73
	v_cvt_pk_bf16_f32 v69, v74, v75
	v_cvt_pk_bf16_f32 v70, v76, v77
	v_cvt_pk_bf16_f32 v71, v78, v79
	s_waitcnt lgkmcnt(2)
	v_mfma_f32_32x32x16_bf16 v[48:63], v[164:167], v[64:67], v[48:63]
	ds_read_b128 v[164:167], v145
	v_mfma_f32_32x32x16_bf16 v[32:47], v[168:171], v[64:67], v[32:47]
	ds_read_b128 v[168:171], v145 offset:4096
	s_waitcnt lgkmcnt(2)
	v_mfma_f32_32x32x16_bf16 v[16:31], v[176:179], v[64:67], v[16:31]
	ds_read_b128 v[176:179], v145 offset:8192
	v_mfma_f32_32x32x16_bf16 v[0:15], v[226:229], v[64:67], v[0:15]
	ds_read_b128 v[226:229], v145 offset:12288
	ds_read_b128 v[202:205], v128 offset:8192
	ds_read_b128 v[206:209], v129 offset:8192
	ds_read_b128 v[210:213], v130 offset:8192
	ds_read_b128 v[214:217], v131 offset:8192
	ds_read_b128 v[218:221], v132 offset:8192
	ds_read_b128 v[222:225], v133 offset:8192
	s_cmp_gt_i32 s33, s97
	s_cbranch_scc1 .Lat_mask_a

.Lat_resc_a_ret:
	v_fma_f32 v80, v80, s84, -v199
	v_exp_f32_e32 v80, v80
	v_fma_f32 v81, v81, s84, -v199
	v_exp_f32_e32 v81, v81
	v_add_f32_e32 v200, v200, v80
	v_fma_f32 v82, v82, s84, -v199
	v_exp_f32_e32 v82, v82
	v_add_f32_e32 v200, v200, v81
	s_waitcnt lgkmcnt(4)
	v_mfma_f32_32x32x16_bf16 v[64:79], v[202:205], v[96:99], 0
	ds_read_b128 v[202:205], v134 offset:8192
	v_fma_f32 v83, v83, s84, -v199
	v_exp_f32_e32 v83, v83
	v_add_f32_e32 v200, v200, v82
	v_fma_f32 v84, v84, s84, -v199
	v_mfma_f32_32x32x16_bf16 v[64:79], v[206:209], v[100:103], v[64:79]
	ds_read_b128 v[206:209], v135 offset:8192
	v_exp_f32_e32 v84, v84
	v_add_f32_e32 v200, v200, v83
	v_fma_f32 v85, v85, s84, -v199
	v_exp_f32_e32 v85, v85
	s_waitcnt lgkmcnt(4)
	v_mfma_f32_32x32x16_bf16 v[64:79], v[210:213], v[104:107], v[64:79]
	ds_read_b128 v[210:213], v136 offset:4096
	v_add_f32_e32 v200, v200, v84
	v_fma_f32 v86, v86, s84, -v199
	v_exp_f32_e32 v86, v86
	v_add_f32_e32 v200, v200, v85
	v_mfma_f32_32x32x16_bf16 v[64:79], v[214:217], v[108:111], v[64:79]
	ds_read_b128 v[214:217], v137 offset:4096
	v_fma_f32 v87, v87, s84, -v199
	v_exp_f32_e32 v87, v87
	v_add_f32_e32 v200, v200, v86
	v_fma_f32 v88, v88, s84, -v199
	s_waitcnt lgkmcnt(4)
	v_mfma_f32_32x32x16_bf16 v[64:79], v[218:221], v[112:115], v[64:79]
	ds_read_b128 v[218:221], v138 offset:4096
	v_exp_f32_e32 v88, v88
	v_add_f32_e32 v200, v200, v87
	v_fma_f32 v89, v89, s84, -v199
	v_exp_f32_e32 v89, v89
	v_mfma_f32_32x32x16_bf16 v[64:79], v[222:225], v[116:119], v[64:79]
	ds_read_b128 v[222:225], v139 offset:4096
	v_add_f32_e32 v200, v200, v88
	v_fma_f32 v90, v90, s84, -v199
	v_exp_f32_e32 v90, v90
	v_add_f32_e32 v200, v200, v89
	s_waitcnt lgkmcnt(4)
	v_mfma_f32_32x32x16_bf16 v[64:79], v[202:205], v[120:123], v[64:79]
	ds_read_b128 v[164:167], v140
	v_fma_f32 v91, v91, s84, -v199
	v_exp_f32_e32 v91, v91
	v_add_f32_e32 v200, v200, v90
	v_fma_f32 v92, v92, s84, -v199
	v_mfma_f32_32x32x16_bf16 v[64:79], v[206:209], v[124:127], v[64:79]
	ds_read_b128 v[168:171], v140 offset:4096
	v_exp_f32_e32 v92, v92
	v_add_f32_e32 v200, v200, v91
	v_fma_f32 v93, v93, s84, -v199
	v_exp_f32_e32 v93, v93
	s_waitcnt lgkmcnt(4)
	v_mfma_f32_32x32x16_bf16 v[64:79], v[210:213], v[160:163], v[64:79]
	ds_read_b128 v[176:179], v140 offset:8192
	v_add_f32_e32 v200, v200, v92
	v_fma_f32 v94, v94, s84, -v199
	v_exp_f32_e32 v94, v94
	v_add_f32_e32 v200, v200, v93
	v_mfma_f32_32x32x16_bf16 v[64:79], v[214:217], v[152:155], v[64:79]
	ds_read_b128 v[226:229], v140 offset:12288
	v_fma_f32 v95, v95, s84, -v199
	v_exp_f32_e32 v95, v95
	v_add_f32_e32 v200, v200, v94
	v_add_f32_e32 v200, v200, v95
	s_waitcnt lgkmcnt(4)
	v_mfma_f32_32x32x16_bf16 v[64:79], v[218:221], v[156:159], v[64:79]
	v_cvt_pk_bf16_f32 v80, v80, v81
	v_cvt_pk_bf16_f32 v81, v82, v83
	v_cvt_pk_bf16_f32 v82, v84, v85
	v_cvt_pk_bf16_f32 v83, v86, v87
	v_mfma_f32_32x32x16_bf16 v[64:79], v[222:225], v[148:151], v[64:79]
	v_cvt_pk_bf16_f32 v84, v88, v89
	v_cvt_pk_bf16_f32 v85, v90, v91
	v_cvt_pk_bf16_f32 v86, v92, v93
	v_cvt_pk_bf16_f32 v87, v94, v95
	s_waitcnt lgkmcnt(2)
	v_mfma_f32_32x32x16_bf16 v[48:63], v[164:167], v[80:83], v[48:63]
	ds_read_b128 v[164:167], v141
	v_mfma_f32_32x32x16_bf16 v[32:47], v[168:171], v[80:83], v[32:47]
	ds_read_b128 v[168:171], v141 offset:4096
	s_waitcnt lgkmcnt(2)
	v_mfma_f32_32x32x16_bf16 v[16:31], v[176:179], v[80:83], v[16:31]
	ds_read_b128 v[176:179], v141 offset:8192
	v_mfma_f32_32x32x16_bf16 v[0:15], v[226:229], v[80:83], v[0:15]
	ds_read_b128 v[226:229], v141 offset:12288
	s_cmp_gt_i32 s33, s97
	s_cbranch_scc1 .Lat_mask_b

.Lat_resc_b_ret:
	v_xor_b32_e32 v128, 0x4000, v128
	v_xor_b32_e32 v129, 0x4000, v129
	v_xor_b32_e32 v130, 0x4000, v130
	v_xor_b32_e32 v131, 0x4000, v131
	v_xor_b32_e32 v132, 0x4000, v132
	v_xor_b32_e32 v133, 0x4000, v133
	v_xor_b32_e32 v134, 0x4000, v134
	v_xor_b32_e32 v135, 0x4000, v135
	v_xor_b32_e32 v136, 0x2000, v136
	v_xor_b32_e32 v137, 0x2000, v137
	v_xor_b32_e32 v138, 0x2000, v138
	v_xor_b32_e32 v139, 0x2000, v139
	v_xor_b32_e32 v144, 64, v140
	v_xor_b32_e32 v145, 64, v141
	s_add_i32 s4, s52, 1
	s_mov_b32 s5, 0xffff8000
	s_cmp_lg_u32 s52, 2
	s_cselect_b32 s52, s4, 0
	s_cselect_b32 s4, 0x4000, s5
	v_add_u32_e32 v140, s4, v140
	v_add_u32_e32 v141, s4, v141
	s_add_i32 s33, s33, 64
	v_subrev_u32_e32 v197, 64, v197
	s_mov_b32 s0, s54
	s_cmp_eq_u32 s53, s54
	s_waitcnt vmcnt(0) lgkmcnt(0)
	s_barrier
	s_cbranch_scc0 .LBB0_1340
	v_fma_f32 v64, v64, s84, -v199
	v_exp_f32_e32 v64, v64
	v_fma_f32 v65, v65, s84, -v199
	v_exp_f32_e32 v65, v65
	v_add_f32_e32 v200, v200, v64
	v_fma_f32 v66, v66, s84, -v199
	v_exp_f32_e32 v66, v66
	v_add_f32_e32 v200, v200, v65
	v_fma_f32 v67, v67, s84, -v199
	v_exp_f32_e32 v67, v67
	v_add_f32_e32 v200, v200, v66
	v_fma_f32 v68, v68, s84, -v199
	v_exp_f32_e32 v68, v68
	v_add_f32_e32 v200, v200, v67
	v_fma_f32 v69, v69, s84, -v199
	v_exp_f32_e32 v69, v69
	v_add_f32_e32 v200, v200, v68
	v_fma_f32 v70, v70, s84, -v199
	v_exp_f32_e32 v70, v70
	v_add_f32_e32 v200, v200, v69
	v_fma_f32 v71, v71, s84, -v199
	v_exp_f32_e32 v71, v71
	v_add_f32_e32 v200, v200, v70
	v_fma_f32 v72, v72, s84, -v199
	v_exp_f32_e32 v72, v72
	v_add_f32_e32 v200, v200, v71
	v_fma_f32 v73, v73, s84, -v199
	v_exp_f32_e32 v73, v73
	v_add_f32_e32 v200, v200, v72
	v_fma_f32 v74, v74, s84, -v199
	v_exp_f32_e32 v74, v74
	v_add_f32_e32 v200, v200, v73
	v_fma_f32 v75, v75, s84, -v199
	v_exp_f32_e32 v75, v75
	v_add_f32_e32 v200, v200, v74
	v_fma_f32 v76, v76, s84, -v199
	v_exp_f32_e32 v76, v76
	v_add_f32_e32 v200, v200, v75
	v_fma_f32 v77, v77, s84, -v199
	v_exp_f32_e32 v77, v77
	v_add_f32_e32 v200, v200, v76
	v_fma_f32 v78, v78, s84, -v199
	v_exp_f32_e32 v78, v78
	v_add_f32_e32 v200, v200, v77
	v_fma_f32 v79, v79, s84, -v199
	v_exp_f32_e32 v79, v79
	v_add_f32_e32 v200, v200, v78
	v_add_f32_e32 v200, v200, v79
	v_cvt_pk_bf16_f32 v236, v64, v65
	v_cvt_pk_bf16_f32 v237, v66, v67
	v_cvt_pk_bf16_f32 v238, v68, v69
	v_cvt_pk_bf16_f32 v239, v70, v71
	v_cvt_pk_bf16_f32 v240, v72, v73
	v_cvt_pk_bf16_f32 v241, v74, v75
	v_cvt_pk_bf16_f32 v242, v76, v77
	v_cvt_pk_bf16_f32 v243, v78, v79
	v_mov_b32_e32 v68, v236
	v_mov_b32_e32 v69, v237
	v_mov_b32_e32 v70, v238
	v_mov_b32_e32 v71, v239
	v_mov_b32_e32 v64, v240
	v_mov_b32_e32 v65, v241
	v_mov_b32_e32 v66, v242
	v_mov_b32_e32 v67, v243
	s_branch .LBB0_1332
.Lat_idle:
	s_cmp_lg_u32 s55, 0
	s_cbranch_scc1 .Lat_idle_go
	s_mov_b32 s55, 1
	v_fma_f32 v64, v64, s84, -v199
	v_exp_f32_e32 v64, v64
	v_fma_f32 v65, v65, s84, -v199
	v_exp_f32_e32 v65, v65
	v_add_f32_e32 v200, v200, v64
	v_fma_f32 v66, v66, s84, -v199
	v_exp_f32_e32 v66, v66
	v_add_f32_e32 v200, v200, v65
	v_fma_f32 v67, v67, s84, -v199
	v_exp_f32_e32 v67, v67
	v_add_f32_e32 v200, v200, v66
	v_fma_f32 v68, v68, s84, -v199
	v_exp_f32_e32 v68, v68
	v_add_f32_e32 v200, v200, v67
	v_fma_f32 v69, v69, s84, -v199
	v_exp_f32_e32 v69, v69
	v_add_f32_e32 v200, v200, v68
	v_fma_f32 v70, v70, s84, -v199
	v_exp_f32_e32 v70, v70
	v_add_f32_e32 v200, v200, v69
	v_fma_f32 v71, v71, s84, -v199
	v_exp_f32_e32 v71, v71
	v_add_f32_e32 v200, v200, v70
	v_fma_f32 v72, v72, s84, -v199
	v_exp_f32_e32 v72, v72
	v_add_f32_e32 v200, v200, v71
	v_fma_f32 v73, v73, s84, -v199
	v_exp_f32_e32 v73, v73
	v_add_f32_e32 v200, v200, v72
	v_fma_f32 v74, v74, s84, -v199
	v_exp_f32_e32 v74, v74
	v_add_f32_e32 v200, v200, v73
	v_fma_f32 v75, v75, s84, -v199
	v_exp_f32_e32 v75, v75
	v_add_f32_e32 v200, v200, v74
	v_fma_f32 v76, v76, s84, -v199
	v_exp_f32_e32 v76, v76
	v_add_f32_e32 v200, v200, v75
	v_fma_f32 v77, v77, s84, -v199
	v_exp_f32_e32 v77, v77
	v_add_f32_e32 v200, v200, v76
	v_fma_f32 v78, v78, s84, -v199
	v_exp_f32_e32 v78, v78
	v_add_f32_e32 v200, v200, v77
	v_fma_f32 v79, v79, s84, -v199
	v_exp_f32_e32 v79, v79
	v_add_f32_e32 v200, v200, v78
	v_add_f32_e32 v200, v200, v79
	v_cvt_pk_bf16_f32 v64, v64, v65
	v_cvt_pk_bf16_f32 v65, v66, v67
	v_cvt_pk_bf16_f32 v66, v68, v69
	v_cvt_pk_bf16_f32 v67, v70, v71
	v_cvt_pk_bf16_f32 v68, v72, v73
	v_cvt_pk_bf16_f32 v69, v74, v75
	v_cvt_pk_bf16_f32 v70, v76, v77
	v_cvt_pk_bf16_f32 v71, v78, v79
	ds_read_b128 v[164:167], v144
	ds_read_b128 v[168:171], v144 offset:4096
	ds_read_b128 v[176:179], v144 offset:8192
	ds_read_b128 v[226:229], v144 offset:12288
	s_waitcnt lgkmcnt(0)
	v_mfma_f32_32x32x16_bf16 v[48:63], v[164:167], v[64:67], v[48:63]
	v_mfma_f32_32x32x16_bf16 v[32:47], v[168:171], v[64:67], v[32:47]
	v_mfma_f32_32x32x16_bf16 v[16:31], v[176:179], v[64:67], v[16:31]
	v_mfma_f32_32x32x16_bf16 v[0:15], v[226:229], v[64:67], v[0:15]
	ds_read_b128 v[164:167], v145
	ds_read_b128 v[168:171], v145 offset:4096
	ds_read_b128 v[176:179], v145 offset:8192
	ds_read_b128 v[226:229], v145 offset:12288
	s_waitcnt lgkmcnt(0)
	v_mfma_f32_32x32x16_bf16 v[48:63], v[164:167], v[68:71], v[48:63]
	v_mfma_f32_32x32x16_bf16 v[32:47], v[168:171], v[68:71], v[32:47]
	v_mfma_f32_32x32x16_bf16 v[16:31], v[176:179], v[68:71], v[16:31]
	v_mfma_f32_32x32x16_bf16 v[0:15], v[226:229], v[68:71], v[0:15]
	s_nop 7
	v_mov_b32_e32 v64, 0xff61b1e6
	v_mov_b32_e32 v65, v64
	v_mov_b32_e32 v66, v64
	v_mov_b32_e32 v67, v64
	v_mov_b32_e32 v68, v64
	v_mov_b32_e32 v69, v64
	v_mov_b32_e32 v70, v64
	v_mov_b32_e32 v71, v64
	v_mov_b32_e32 v72, v64
	v_mov_b32_e32 v73, v64
	v_mov_b32_e32 v74, v64
	v_mov_b32_e32 v75, v64
	v_mov_b32_e32 v76, v64
	v_mov_b32_e32 v77, v64
	v_mov_b32_e32 v78, v64
	v_mov_b32_e32 v79, v64

.Lat_mask_a:
	s_nop 7
	v_cmp_gt_i32_e64 s[4:5], 0, v197
	v_cmp_gt_i32_e64 s[6:7], 1, v197
	v_cmp_gt_i32_e64 s[8:9], 2, v197
	v_cmp_gt_i32_e64 s[10:11], 3, v197
	v_cmp_gt_i32_e64 s[12:13], 4, v197
	v_cmp_gt_i32_e64 s[14:15], 5, v197
	v_cmp_gt_i32_e64 s[16:17], 6, v197
	v_cmp_gt_i32_e64 s[18:19], 7, v197
	v_cndmask_b32_e64 v80, v80, v192, s[4:5]
	v_cndmask_b32_e64 v81, v81, v192, s[6:7]
	v_cndmask_b32_e64 v82, v82, v192, s[8:9]
	v_cndmask_b32_e64 v83, v83, v192, s[10:11]
	v_cndmask_b32_e64 v84, v84, v192, s[12:13]
	v_cndmask_b32_e64 v85, v85, v192, s[14:15]
	v_cndmask_b32_e64 v86, v86, v192, s[16:17]
	v_cndmask_b32_e64 v87, v87, v192, s[18:19]
	v_cmp_gt_i32_e64 s[4:5], 16, v197
	v_cmp_gt_i32_e64 s[6:7], 17, v197
	v_cmp_gt_i32_e64 s[8:9], 18, v197
	v_cmp_gt_i32_e64 s[10:11], 19, v197
	v_cmp_gt_i32_e64 s[12:13], 20, v197
	v_cmp_gt_i32_e64 s[14:15], 21, v197
	v_cmp_gt_i32_e64 s[16:17], 22, v197
	v_cmp_gt_i32_e64 s[18:19], 23, v197
	v_cndmask_b32_e64 v88, v88, v192, s[4:5]
	v_cndmask_b32_e64 v89, v89, v192, s[6:7]
	v_cndmask_b32_e64 v90, v90, v192, s[8:9]
	v_cndmask_b32_e64 v91, v91, v192, s[10:11]
	v_cndmask_b32_e64 v92, v92, v192, s[12:13]
	v_cndmask_b32_e64 v93, v93, v192, s[14:15]
	v_cndmask_b32_e64 v94, v94, v192, s[16:17]
	v_cndmask_b32_e64 v95, v95, v192, s[18:19]
	s_branch .Lat_mask_a_ret
.Lat_mask_b:
	s_nop 7
	v_cmp_gt_i32_e64 s[4:5], 32, v197
	v_cmp_gt_i32_e64 s[6:7], 33, v197
	v_cmp_gt_i32_e64 s[8:9], 34, v197
	v_cmp_gt_i32_e64 s[10:11], 35, v197
	v_cmp_gt_i32_e64 s[12:13], 36, v197
	v_cmp_gt_i32_e64 s[14:15], 37, v197
	v_cmp_gt_i32_e64 s[16:17], 38, v197
	v_cmp_gt_i32_e64 s[18:19], 39, v197
	v_cndmask_b32_e64 v64, v64, v192, s[4:5]
	v_cndmask_b32_e64 v65, v65, v192, s[6:7]
	v_cndmask_b32_e64 v66, v66, v192, s[8:9]
	v_cndmask_b32_e64 v67, v67, v192, s[10:11]
	v_cndmask_b32_e64 v68, v68, v192, s[12:13]
	v_cndmask_b32_e64 v69, v69, v192, s[14:15]
	v_cndmask_b32_e64 v70, v70, v192, s[16:17]
	v_cndmask_b32_e64 v71, v71, v192, s[18:19]
	v_cmp_gt_i32_e64 s[4:5], 48, v197
	v_cmp_gt_i32_e64 s[6:7], 49, v197
	v_cmp_gt_i32_e64 s[8:9], 50, v197
	v_cmp_gt_i32_e64 s[10:11], 51, v197
	v_cmp_gt_i32_e64 s[12:13], 52, v197
	v_cmp_gt_i32_e64 s[14:15], 53, v197
	v_cmp_gt_i32_e64 s[16:17], 54, v197
	v_cmp_gt_i32_e64 s[18:19], 55, v197
	v_cndmask_b32_e64 v72, v72, v192, s[4:5]
	v_cndmask_b32_e64 v73, v73, v192, s[6:7]
	v_cndmask_b32_e64 v74, v74, v192, s[8:9]
	v_cndmask_b32_e64 v75, v75, v192, s[10:11]
	v_cndmask_b32_e64 v76, v76, v192, s[12:13]
	v_cndmask_b32_e64 v77, v77, v192, s[14:15]
	v_cndmask_b32_e64 v78, v78, v192, s[16:17]
	v_cndmask_b32_e64 v79, v79, v192, s[18:19]
	s_branch .Lat_mask_b_ret
